# prep phase: 4th weight strip (W_pm/W_pa/W_out) converted after arriving at the first grid barrier; wait deferred past it
# baseline (speedup 1.0000x reference)
; #define LAS __attribute__((address_space(3)))
; __device__ __forceinline__ void p0_prep(const Params& p, LAS unsigned char* lds) {
;     const int tid = threadIdx.x, G = gridDim.x, bid = blockIdx.x, lane = tid & 63, wid = tid >> 6;
;     unsigned char* ws = p.ws;
;     LAS float* tile = (LAS float*)lds;
;     LAS float* WG = (LAS float*)(lds + 32768);
;     for (int i = tid; i < 2048; i += 512) { const int k = i >> 1, hf = i & 1; *(LAS f32x4*)(WG + k * 8 + hf * 4) = *(const f32x4*)(p.w_in + (size_t)k * INW + 5120 + hf * 4); }
; __global__ void __launch_bounds__(512, 2) mega_fwd(Params p) {
;     ...
;     if (IN(0)) { for (int rep = 0; rep < REP0; ++rep) p0_prep(p, lds); }
.LBB0_19:
	s_mov_b32 s101, 0
	s_cmp_lt_i32 s90, 1
	s_cselect_b64 s[0:1], -1, 0
	s_cmp_gt_i32 s91, 0
	s_cselect_b64 s[2:3], -1, 0
	s_and_b64 s[10:11], s[0:1], s[2:3]
	s_andn2_b64 vcc, exec, s[10:11]
	v_and_b32_e32 v190, 1, v212
	s_cbranch_vccnz .LBB0_60
.Lp0_reenter:
	s_cmp_eq_u32 s101, 2
	s_cbranch_scc1 .Lp0_in
	s_mov_b32 s101, 0
	s_movk_i32 s100, 0x39f
	s_cmp_eq_u32 s82, 0x100
	s_cbranch_scc0 .Lp0_in
	s_mov_b32 s101, 3
	s_movk_i32 s100, 0x2ff
.Lp0_in:
	v_lshrrev_b32_e32 v0, 1, v212
	v_lshlrev_b32_e32 v4, 4, v190
	v_lshl_or_b32 v1, v0, 5, v4
	v_add_u32_e32 v1, 0, v1
	v_add_u32_e32 v3, 0x8000, v1
	v_mul_hi_u32_u24_e32 v1, 0xc020, v0
	v_mul_u32_u24_e32 v0, 0xc020, v0
	v_readlane_b32 s12, v254, 4
	v_or_b32_e32 v0, v0, v4
	v_readlane_b32 s16, v254, 8
	v_readlane_b32 s17, v254, 9
	s_mov_b64 s[0:1], 0x5000
	v_add_u32_e32 v2, 0xfffffe00, v212
	v_lshl_add_u64 v[0:1], s[16:17], 0, v[0:1]
	v_lshl_add_u64 v[0:1], v[0:1], 0, s[0:1]
	s_mov_b64 s[0:1], 0
	s_mov_b64 s[2:3], 0xc02000
	s_movk_i32 s4, 0x5ff
	v_readlane_b32 s13, v254, 5
	v_readlane_b32 s14, v254, 6
	v_readlane_b32 s15, v254, 7
	v_readlane_b32 s18, v254, 10
	v_readlane_b32 s19, v254, 11
	v_readlane_b32 s20, v254, 12
	v_readlane_b32 s21, v254, 13
	v_readlane_b32 s22, v254, 14
	v_readlane_b32 s23, v254, 15
	v_readlane_b32 s24, v254, 16
	v_readlane_b32 s25, v254, 17
	v_readlane_b32 s26, v254, 18
	v_readlane_b32 s27, v254, 19

; __device__ __forceinline__ void p0_prep(const Params& p, LAS unsigned char* lds) {
;     ...
;     for (int tI = bid; tI < 928; tI += G) {
;         const float* src; bf16_t* dst; int ldn, Kdim, ns, kt, srccol;
;         int u = tI;
;         if (u < 768) { ns = u >> 4; kt = u & 15; src = p.w_in; ldn = INW; Kdim = 1024; dst = (bf16_t*)(ws + WS_WIN); srccol = ns * 256 + (ns >= 20 ? 8 : 0); }
;         else if (u < 832) { u -= 768; ns = u >> 4; kt = u & 15; src = p.w_pm; ldn = 1024; Kdim = 1024; dst = (bf16_t*)(ws + WS_WPM); srccol = ns * 256; }
;         else if (u < 864) { u -= 832; ns = u >> 3; kt = u & 7; src = p.w_pa; ldn = 1024; Kdim = 512; dst = (bf16_t*)(ws + WS_WPA); srccol = ns * 256; }
;         else { u -= 864; ns = u >> 4; kt = u & 15; src = p.w_out; ldn = 1024; Kdim = 1024; dst = (bf16_t*)(ws + WS_WOUT); srccol = ns * 256; }
;         float4 v[8];
; #pragma unroll
;         for (int i = 0; i < 8; ++i) { const int idx = tid + 512 * i; const int k = idx >> 6, n4 = idx & 63; const f32x4 t = __builtin_nontemporal_load((const f32x4*)(src + (size_t)(kt * 64 + k) * ldn + srccol + 4 * n4)); v[i] = make_float4(t[0], t[1], t[2], t[3]); }
; #pragma unroll
;         for (int i = 0; i < 8; ++i) { const int idx = tid + 512 * i; const int k = idx >> 6, n4 = idx & 63;
;             strip[k * 257 + 4 * n4 + 0] = v[i].x; strip[k * 257 + 4 * n4 + 1] = v[i].y; strip[k * 257 + 4 * n4 + 2] = v[i].z; strip[k * 257 + 4 * n4 + 3] = v[i].w; }
;         __syncthreads();
; #pragma unroll
;         for (int j = 0; j < 4; ++j) { const int piece = tid + 512 * j; const int n = piece >> 3, kv = piece & 7; float f[8];
; #pragma unroll
;             for (int e = 0; e < 8; ++e) f[e] = strip[(kv * 8 + e) * 257 + n];
;             *(u32x4*)(dst + (size_t)(ns * 256 + n) * Kdim + kt * 64 + kv * 8) = pack8(f); }
;         __syncthreads();
.LBB0_25:
	s_ashr_i32 s19, s18, 31
	s_lshl_b32 s17, s25, 6
	s_lshl_b64 s[18:19], s[18:19], 2
	s_add_u32 s14, s14, s18
	s_addc_u32 s15, s15, s19
	v_or_b32_e32 v30, s17, v6
	v_or_b32_e32 v32, s17, v7
	v_or_b32_e32 v38, s17, v8
	v_or_b32_e32 v40, s17, v9
	v_or_b32_e32 v46, s17, v10
	v_or_b32_e32 v48, s17, v11
	v_lshl_add_u64 v[58:59], s[14:15], 0, v[0:1]
	v_mul_hi_u32_u24_e32 v31, s16, v30
	v_mul_u32_u24_e32 v30, s16, v30
	v_mul_hi_u32_u24_e32 v33, s16, v32
	v_mul_u32_u24_e32 v32, s16, v32
	v_mul_hi_u32_u24_e32 v39, s16, v38
	v_mul_u32_u24_e32 v38, s16, v38
	v_mul_hi_u32_u24_e32 v41, s16, v40
	v_mul_u32_u24_e32 v40, s16, v40
	v_mul_hi_u32_u24_e32 v47, s16, v46
	v_mul_u32_u24_e32 v46, s16, v46
	v_mul_hi_u32_u24_e32 v49, s16, v48
	v_mul_u32_u24_e32 v48, s16, v48
	v_lshl_add_u64 v[30:31], v[30:31], 2, v[58:59]
	v_lshl_add_u64 v[34:35], v[32:33], 2, v[58:59]
	v_lshl_add_u64 v[38:39], v[38:39], 2, v[58:59]
	v_lshl_add_u64 v[42:43], v[40:41], 2, v[58:59]
	v_lshl_add_u64 v[46:47], v[46:47], 2, v[58:59]
	v_lshl_add_u64 v[50:51], v[48:49], 2, v[58:59]
	global_load_dwordx4 v[30:33], v[30:31], off nt
	s_nop 0
	global_load_dwordx4 v[34:37], v[34:35], off nt
	s_nop 0
	global_load_dwordx4 v[38:41], v[38:39], off nt
	s_nop 0
	global_load_dwordx4 v[42:45], v[42:43], off nt
	s_nop 0
	global_load_dwordx4 v[46:49], v[46:47], off nt
	s_nop 0
	global_load_dwordx4 v[50:53], v[50:51], off nt
	v_or_b32_e32 v54, s17, v12
	v_mul_hi_u32_u24_e32 v55, s16, v54
	v_mul_u32_u24_e32 v54, s16, v54
	v_lshl_add_u64 v[54:55], v[54:55], 2, v[58:59]
	v_add_u32_e32 v60, s17, v13
	global_load_dwordx4 v[54:57], v[54:55], off nt
	v_mul_hi_u32_u24_e32 v61, s16, v60
	v_mul_u32_u24_e32 v60, s16, v60
	v_lshl_add_u64 v[58:59], v[60:61], 2, v[58:59]
	global_load_dwordx4 v[58:61], v[58:59], off nt
	v_add_u32_e32 v62, s24, v4
	v_ashrrev_i32_e32 v64, 31, v62
	v_mul_lo_u32 v65, s7, v62
	v_mad_u64_u32 v[62:63], s[14:15], s6, v62, 0
	s_lshl_b32 s14, s25, 7
	s_add_u32 s8, s8, s14
	v_mul_lo_u32 v64, s6, v64
	s_addc_u32 s9, s9, 0
	v_add3_u32 v63, v63, v64, v65
	v_lshl_add_u64 v[64:65], s[8:9], 0, v[2:3]
	s_add_i32 s23, s23, s82
	s_add_i32 s22, s22, s12
	s_add_i32 s20, s20, s21
	s_cmp_gt_i32 s23, s100
	s_waitcnt vmcnt(7)
	ds_write2_b32 v16, v30, v31 offset1:1
	ds_write2_b32 v16, v32, v33 offset0:2 offset1:3
	s_waitcnt vmcnt(6)
	ds_write2_b32 v17, v34, v35 offset1:1
	ds_write2_b32 v17, v36, v37 offset0:2 offset1:3
	s_waitcnt vmcnt(5)
	ds_write2_b32 v18, v38, v39 offset1:1
	ds_write2_b32 v18, v40, v41 offset0:2 offset1:3
	s_waitcnt vmcnt(4)
	ds_write2_b32 v19, v42, v43 offset1:1
	ds_write2_b32 v19, v44, v45 offset0:2 offset1:3
	s_waitcnt vmcnt(3)
	ds_write2_b32 v20, v46, v47 offset1:1
	ds_write2_b32 v21, v48, v49 offset1:1
	s_waitcnt vmcnt(2)
	ds_write2_b32 v22, v50, v51 offset1:1
	ds_write2_b32 v22, v52, v53 offset0:2 offset1:3
	s_waitcnt vmcnt(1)
	ds_write2_b32 v23, v54, v55 offset1:1
	ds_write2_b32 v24, v56, v57 offset1:1
	s_waitcnt vmcnt(0)
	ds_write2_b32 v25, v58, v59 offset1:1
	ds_write2_b32 v25, v60, v61 offset0:2 offset1:3
	s_waitcnt lgkmcnt(0)
	s_barrier
	ds_read_b32 v30, v26
	ds_read_b32 v31, v26 offset:1028
	ds_read_b32 v32, v26 offset:2056
	ds_read_b32 v33, v26 offset:3084
	ds_read_b32 v36, v26 offset:4112
	ds_read_b32 v37, v26 offset:5140
	ds_read_b32 v38, v26 offset:6168
	ds_read_b32 v39, v26 offset:7196
	v_lshl_add_u64 v[34:35], v[62:63], 1, v[64:65]
	s_waitcnt lgkmcnt(6)
	v_cvt_pk_bf16_f32 v30, v30, v31
	s_waitcnt lgkmcnt(4)
	v_cvt_pk_bf16_f32 v31, v32, v33
	s_waitcnt lgkmcnt(2)
	v_cvt_pk_bf16_f32 v32, v36, v37
	s_waitcnt lgkmcnt(0)
	v_cvt_pk_bf16_f32 v33, v38, v39
	ds_read_b32 v36, v27
	ds_read_b32 v37, v27 offset:1028
	ds_read_b32 v38, v27 offset:2056
	ds_read_b32 v39, v27 offset:3084
	ds_read_b32 v40, v27 offset:4112
	ds_read_b32 v41, v27 offset:5140
	ds_read_b32 v42, v27 offset:6168
	ds_read_b32 v43, v27 offset:7196
	global_store_dwordx4 v[34:35], v[30:33], off
	v_add_u32_e32 v34, s24, v14
	v_ashrrev_i32_e32 v35, 31, v34
	s_waitcnt lgkmcnt(6)
	v_cvt_pk_bf16_f32 v30, v36, v37
	v_mul_lo_u32 v36, s6, v35
	v_mul_lo_u32 v37, s7, v34
	v_mad_u64_u32 v[34:35], s[8:9], s6, v34, 0
	v_add3_u32 v35, v35, v36, v37
	s_waitcnt lgkmcnt(4)
	v_cvt_pk_bf16_f32 v31, v38, v39
	s_waitcnt lgkmcnt(2)
	v_cvt_pk_bf16_f32 v32, v40, v41
	s_waitcnt lgkmcnt(0)
	v_cvt_pk_bf16_f32 v33, v42, v43
	v_lshl_add_u64 v[34:35], v[34:35], 1, v[64:65]
	ds_read_b32 v36, v28
	ds_read_b32 v37, v28 offset:1028
	ds_read_b32 v38, v28 offset:2056
	ds_read_b32 v39, v28 offset:3084
	ds_read_b32 v40, v28 offset:4112
	ds_read_b32 v41, v28 offset:5140
	ds_read_b32 v42, v28 offset:6168
	ds_read_b32 v43, v28 offset:7196
	global_store_dwordx4 v[34:35], v[30:33], off
	v_add_u32_e32 v34, s24, v15
	v_ashrrev_i32_e32 v35, 31, v34
	s_waitcnt lgkmcnt(6)
	v_cvt_pk_bf16_f32 v30, v36, v37
	v_mul_lo_u32 v36, s6, v35
	v_mul_lo_u32 v37, s7, v34
	v_mad_u64_u32 v[34:35], s[8:9], s6, v34, 0
	v_add3_u32 v35, v35, v36, v37
	s_waitcnt lgkmcnt(4)
	v_cvt_pk_bf16_f32 v31, v38, v39
	s_waitcnt lgkmcnt(2)
	v_cvt_pk_bf16_f32 v32, v40, v41
	s_waitcnt lgkmcnt(0)
	v_cvt_pk_bf16_f32 v33, v42, v43
	v_lshl_add_u64 v[34:35], v[34:35], 1, v[64:65]
	ds_read_b32 v36, v29
	ds_read_b32 v37, v29 offset:1028
	ds_read_b32 v38, v29 offset:2056
	ds_read_b32 v39, v29 offset:3084
	ds_read_b32 v40, v29 offset:4112
	ds_read_b32 v41, v29 offset:5140
	ds_read_b32 v42, v29 offset:6168
	ds_read_b32 v43, v29 offset:7196
	global_store_dwordx4 v[34:35], v[30:33], off
	v_add_u32_e32 v34, s24, v5
	v_ashrrev_i32_e32 v35, 31, v34
	s_waitcnt lgkmcnt(6)
	v_cvt_pk_bf16_f32 v30, v36, v37
	v_mul_lo_u32 v36, s6, v35
	v_mul_lo_u32 v37, s7, v34
	v_mad_u64_u32 v[34:35], s[6:7], s6, v34, 0
	v_add3_u32 v35, v35, v36, v37
	s_waitcnt lgkmcnt(4)
	v_cvt_pk_bf16_f32 v31, v38, v39
	s_waitcnt lgkmcnt(2)
	v_cvt_pk_bf16_f32 v32, v40, v41
	s_waitcnt lgkmcnt(0)
	v_cvt_pk_bf16_f32 v33, v42, v43
	v_lshl_add_u64 v[34:35], v[34:35], 1, v[64:65]
	global_store_dwordx4 v[34:35], v[30:33], off
	s_barrier
	s_cbranch_scc1 .LBB0_37

; #define LAS __attribute__((address_space(3)))
; __device__ __forceinline__ void p0_prep(const Params& p, LAS unsigned char* lds) {
;     ...
;     __syncthreads();
;     bf16_t* H = (bf16_t*)((unsigned char*)p.out + OUT_H);
;     float* GATES = (float*)(ws + WS_GATES);
;     const float bias_l = p.b_if[((lane >> 5) & 1) * 4 + ((lane >> 4) & 1) * 2 + ((lane >> 3) & 1)];
;     for (int row0 = (bid * 8 + wid) * 2; row0 < T_TOK; row0 += G * 16) {
;         float4 v[2][4];
; #pragma unroll
;         for (int rr = 0; rr < 2; ++rr)
; #pragma unroll
;             for (int i = 0; i < 4; ++i) { const f32x4 t = __builtin_nontemporal_load((const f32x4*)(p.x + (size_t)(row0 + rr) * 1024) + (i * 64 + lane)); v[rr][i] = make_float4(t[0], t[1], t[2], t[3]); }
; #pragma unroll
;         for (int rr = 0; rr < 2; ++rr) {
;             const int row = row0 + rr;
;             float ss = 0.f;
; #pragma unroll
;             for (int i = 0; i < 4; ++i) ss += v[rr][i].x * v[rr][i].x + v[rr][i].y * v[rr][i].y + v[rr][i].z * v[rr][i].z + v[rr][i].w * v[rr][i].w;
;             ss = wave_sum(ss);
;             const float rstd = rsqrtf(ss * (1.0f / 1024.0f) + EPS);
;             float g[8];
; #pragma unroll
;             for (int j = 0; j < 8; ++j) g[j] = 0.f;
; #pragma unroll
;             for (int i = 0; i < 4; ++i) {
;                 const float4 pw = ((const float4*)p.pre_w)[i * 64 + lane];
;                 float hv[4] = {v[rr][i].x * rstd * pw.x, v[rr][i].y * rstd * pw.y, v[rr][i].z * rstd * pw.z, v[rr][i].w * rstd * pw.w};
;                 u32x2 w; w.x = cvt_pk_bf16(hv[0], hv[1]); w.y = cvt_pk_bf16(hv[2], hv[3]);
;                 *(u32x2*)(H + (size_t)row * 1024 + (i * 64 + lane) * 4) = w;
; #pragma unroll
;                 for (int e = 0; e < 4; ++e) {
;                     const int k = (i * 64 + lane) * 4 + e;
;                     const f32x4 wa = *(const LAS f32x4*)(WG + k * 8), wb = *(const LAS f32x4*)(WG + k * 8 + 4);
;                     g[0] += hv[e] * wa[0]; g[1] += hv[e] * wa[1]; g[2] += hv[e] * wa[2]; g[3] += hv[e] * wa[3];
;                     g[4] += hv[e] * wb[0]; g[5] += hv[e] * wb[1]; g[6] += hv[e] * wb[2]; g[7] += hv[e] * wb[3];
;                 }
;             }
;             const bool h32 = (lane & 32) != 0, h16 = (lane & 16) != 0, h8 = (lane & 8) != 0;
;             float t4[4], t2[2];
; #pragma unroll
.LBB0_37:
	s_cmp_eq_u32 s101, 2
	s_cbranch_scc1 .Lp0_back
	v_lshrrev_b32_e32 v0, 5, v212
	v_and_b32_e32 v0, 30, v0
	v_add_u32_e32 v160, s13, v0
	s_movk_i32 s0, 0x4000
	v_cmp_gt_i32_e32 vcc, s0, v160
	s_waitcnt lgkmcnt(0)
	s_barrier
	s_and_saveexec_b64 s[14:15], vcc
	s_cbranch_execz .LBB0_48
	v_bfe_u32 v0, v212, 3, 3
	v_readlane_b32 s36, v254, 4
	v_lshlrev_b32_e32 v36, 2, v0
	v_readlane_b32 s42, v254, 10
	v_readlane_b32 s43, v254, 11
	v_and_b32_e32 v1, 32, v212
	v_cmp_eq_u32_e32 vcc, 0, v1
	v_and_b32_e32 v1, 7, v212
	v_cmp_eq_u32_e64 s[6:7], 0, v1
	v_mbcnt_lo_u32_b32 v1, -1, 0
	global_load_dword v172, v36, s[42:43]
	v_and_b32_e32 v3, 8, v212
	v_mbcnt_hi_u32_b32 v1, -1, v1
	v_and_b32_e32 v2, 16, v212
	v_cmp_eq_u32_e64 s[4:5], 0, v3
	v_and_b32_e32 v3, 64, v1
	v_cmp_eq_u32_e64 s[2:3], 0, v2
	v_xor_b32_e32 v2, 32, v1
	v_add_u32_e32 v3, 64, v3
	v_cmp_lt_i32_e64 s[0:1], v2, v3
	v_ashrrev_i32_e32 v161, 31, v160
	v_lshlrev_b64 v[34:35], 5, v[160:161]
	v_cndmask_b32_e64 v2, v1, v2, s[0:1]
	v_lshlrev_b32_e32 v173, 2, v2
	v_xor_b32_e32 v2, 16, v1
	v_cmp_lt_i32_e64 s[0:1], v2, v3
	v_or_b32_e32 v34, v34, v36
	v_and_b32_e32 v37, 63, v212
	v_cndmask_b32_e64 v2, v1, v2, s[0:1]
	v_lshlrev_b32_e32 v174, 2, v2
	v_xor_b32_e32 v2, 8, v1
	v_cmp_lt_i32_e64 s[0:1], v2, v3
	v_lshl_add_u64 v[34:35], s[88:89], 0, v[34:35]
	v_lshlrev_b32_e32 v32, 4, v37
	v_cndmask_b32_e64 v2, v1, v2, s[0:1]
	v_lshlrev_b32_e32 v175, 2, v2
	v_xor_b32_e32 v2, 4, v1
	v_cmp_lt_i32_e64 s[0:1], v2, v3
	v_readlane_b32 s37, v254, 5
	v_readlane_b32 s38, v254, 6
	v_cndmask_b32_e64 v2, v1, v2, s[0:1]
	v_lshlrev_b32_e32 v176, 2, v2
	v_xor_b32_e32 v2, 2, v1
	v_cmp_lt_i32_e64 s[0:1], v2, v3
	v_readlane_b32 s39, v254, 7
	v_mov_b32_e32 v33, 0
	v_cndmask_b32_e64 v2, v1, v2, s[0:1]
	v_lshlrev_b32_e32 v177, 2, v2
	v_xor_b32_e32 v2, 1, v1
	v_cmp_lt_i32_e64 s[0:1], v2, v3
	v_lshl_add_u64 v[162:163], s[38:39], 0, v[32:33]
	v_lshl_add_u32 v124, v37, 7, 0
	v_cndmask_b32_e64 v1, v1, v2, s[0:1]
	s_mov_b64 s[0:1], 0x1d00020
	v_lshl_add_u64 v[164:165], v[34:35], 0, s[0:1]
	v_lshlrev_b64 v[34:35], 12, v[160:161]
	v_or_b32_e32 v34, v34, v32
	v_lshl_add_u64 v[32:33], s[36:37], 0, v[34:35]
	s_mov_b64 s[0:1], 0x1000
	v_lshl_add_u64 v[166:167], v[32:33], 0, s[0:1]
	v_lshlrev_b64 v[32:33], 11, v[160:161]
	v_lshl_or_b32 v32, v37, 3, v32
	v_lshl_add_u64 v[32:33], s[74:75], 0, v[32:33]
	s_mov_b64 s[0:1], 0xe00
	v_lshl_add_u64 v[168:169], v[32:33], 0, s[0:1]
	v_lshlrev_b32_e32 v178, 2, v1
	v_cmp_lt_u32_e64 s[8:9], 3, v0
	ds_read_b128 v[0:3], v124 offset:32768
	ds_read_b128 v[4:7], v124 offset:32784
	ds_read_b128 v[8:11], v124 offset:32800
	ds_read_b128 v[12:15], v124 offset:32816
	ds_read_b128 v[16:19], v124 offset:32832
	ds_read_b128 v[20:23], v124 offset:32848
	ds_read_b128 v[24:27], v124 offset:32864
	ds_read_b128 v[28:31], v124 offset:32880
	ds_read_b128 v[32:35], v124 offset:40960
	ds_read_b128 v[36:39], v124 offset:40976
	ds_read_b128 v[40:43], v124 offset:40992
	ds_read_b128 v[44:47], v124 offset:41008
	ds_read_b128 v[48:51], v124 offset:41024
	ds_read_b128 v[52:55], v124 offset:41040
	ds_read_b128 v[56:59], v124 offset:41056
	ds_read_b128 v[60:63], v124 offset:41072
	ds_read_b128 v[64:67], v124 offset:49152
	ds_read_b128 v[68:71], v124 offset:49168
	ds_read_b128 v[72:75], v124 offset:49184
	ds_read_b128 v[76:79], v124 offset:49200
	ds_read_b128 v[80:83], v124 offset:49216
	ds_read_b128 v[84:87], v124 offset:49232
	ds_read_b128 v[88:91], v124 offset:49248
	ds_read_b128 v[92:95], v124 offset:49264
	ds_read_b128 v[96:99], v124 offset:57344
	ds_read_b128 v[100:103], v124 offset:57360
	ds_read_b128 v[104:107], v124 offset:57376
	ds_read_b128 v[108:111], v124 offset:57392
	ds_read_b128 v[112:115], v124 offset:57408
	ds_read_b128 v[116:119], v124 offset:57424
	ds_read_b128 v[120:123], v124 offset:57440
	ds_read_b128 v[124:127], v124 offset:57456
	s_ashr_i32 s13, s12, 31
	s_lshl_b64 s[16:17], s[12:13], 5
	s_lshl_b64 s[18:19], s[12:13], 12
	s_lshl_b64 s[20:21], s[12:13], 11
	s_mov_b64 s[22:23], 0
	v_mov_b32_e32 v161, 0x358637bd
	s_mov_b32 s13, 0x800000
	s_mov_b32 s28, 0xbfb8aa3b
	s_mov_b32 s29, 0xb2a5705f
	s_mov_b32 s30, 0x42ce8ed0
	s_mov_b32 s31, 0xc2b17218
	s_mov_b32 s33, 0x7f800000
	s_mov_b32 s34, 0x3f2aaaab
	v_mov_b32_e32 v179, 0x3ecc95a3
	s_mov_b32 s35, 0x3f317218
	s_mov_b32 s36, 0x33800000
	s_movk_i32 s37, 0x3fff
	v_mov_b32_e32 v180, 0x7f800000
	v_mov_b32_e32 v170, 0x3f317218
	v_readlane_b32 s40, v254, 8
	v_readlane_b32 s41, v254, 9
	v_readlane_b32 s44, v254, 12
	v_readlane_b32 s45, v254, 13
	v_readlane_b32 s46, v254, 14
	v_readlane_b32 s47, v254, 15
	v_readlane_b32 s48, v254, 16
	v_readlane_b32 s49, v254, 17
	v_readlane_b32 s50, v254, 18
	v_readlane_b32 s51, v254, 19
	s_branch .LBB0_41

; __device__ __forceinline__ unsigned xb_ld(unsigned* p)              { return __hip_atomic_load(p, __ATOMIC_RELAXED, __HIP_MEMORY_SCOPE_AGENT); }
; __device__ __forceinline__ void xcd_barrier_complete(unsigned* bar, unsigned x, unsigned& nloc, unsigned& nx) {
;     const unsigned G = gridDim.x * gridDim.y * gridDim.z;
;     unsigned sum, cnt, mine, sp = 0u;
;     for (;;) {
;         sum = 0u; cnt = 0u; mine = 0u;
; #pragma unroll
;         for (unsigned j = 0; j < 16; ++j) { const unsigned c = xb_ld(&bar[XB_XCNT(j)]); sum += c; cnt += (c > 0u) ? 1u : 0u; mine = (j == x) ? c : mine; }
; __device__ __forceinline__ void xcd_barrier(const XcdBarrier& b) {
;     asm volatile("s_waitcnt vmcnt(0)" ::: "memory");
;     __syncthreads();
;     if (threadIdx.x == 0) {
;         unsigned* bar = b.bar;
;         __builtin_amdgcn_s_waitcnt(0);
;         unsigned nloc = b.st[0], nx = b.st[1];
;         if (nloc == 0u) { xcd_barrier_complete(bar, b.x, nloc, nx); b.st[0] = nloc; b.st[1] = nx; }
.LBB0_60:
	s_cmp_gt_i32 s91, 1
	s_cselect_b64 s[0:1], -1, 0
	s_and_b64 s[2:3], s[10:11], s[0:1]
	s_andn2_b64 vcc, exec, s[2:3]
	s_cbranch_vccnz .LBB0_110
	s_cmp_eq_u32 s101, 3
	s_cselect_b32 s101, 1, s101
	s_waitcnt vmcnt(0)
	s_waitcnt lgkmcnt(0)
	s_barrier
	s_mov_b64 s[2:3], exec
	v_readlane_b32 s4, v254, 1
	v_readlane_b32 s5, v254, 2
	s_and_b64 s[4:5], s[2:3], s[4:5]
	s_mov_b64 exec, s[4:5]
	s_cbranch_execz .LBB0_109
	v_mov_b32_e32 v0, s52
	s_waitcnt vmcnt(0) expcnt(0) lgkmcnt(0)
	ds_read_b32 v2, v0
	ds_read_b32 v0, v0 offset:4
	s_waitcnt lgkmcnt(1)
	v_cmp_ne_u32_e32 vcc, 0, v2
	s_cbranch_vccnz .LBB0_77
	v_readlane_b32 s4, v254, 0
	s_mul_i32 s33, s83, s4
	s_add_u32 s4, s88, 0xffc0200
	s_addc_u32 s5, s89, 0
	s_add_u32 s6, s88, 0xffc0400
	s_addc_u32 s7, s89, 0
	s_add_u32 s8, s88, 0xffc0500
	s_addc_u32 s9, s89, 0
	s_add_u32 s10, s88, 0xffc0600
	s_addc_u32 s11, s89, 0
	s_add_u32 s12, s88, 0xffc0700
	s_addc_u32 s13, s89, 0
	s_add_u32 s14, s88, 0xffc0800
	s_addc_u32 s15, s89, 0
	s_add_u32 s16, s88, 0xffc0900
	s_addc_u32 s17, s89, 0
	s_add_u32 s18, s88, 0xffc0a00
	s_addc_u32 s19, s89, 0
	s_add_u32 s20, s88, 0xffc0b00
	s_addc_u32 s21, s89, 0
	s_add_u32 s22, s88, 0xffc0c00
	s_addc_u32 s23, s89, 0
	s_add_u32 s24, s88, 0xffc0d00
	s_addc_u32 s25, s89, 0
	s_add_u32 s26, s88, 0xffc0e00
	s_addc_u32 s27, s89, 0
	s_add_u32 s28, s88, 0xffc0f00
	s_addc_u32 s29, s89, 0
	s_add_u32 s30, s88, 0xffc1000
	s_addc_u32 s31, s89, 0
	s_add_u32 s34, s88, 0xffc1100
	s_addc_u32 s35, s89, 0
	s_add_u32 s36, s88, 0xffc1200
	s_addc_u32 s37, s89, 0
	s_add_u32 s38, s88, 0xffc1300
	s_mul_i32 s33, s33, s82
	s_addc_u32 s39, s89, 0
	s_mov_b32 s46, 1
	v_mov_b32_e32 v16, 0
	s_branch .LBB0_65

; __device__ __forceinline__ unsigned xb_ld(unsigned* p)              { return __hip_atomic_load(p, __ATOMIC_RELAXED, __HIP_MEMORY_SCOPE_AGENT); }
; __device__ __forceinline__ unsigned xb_add(unsigned* p, unsigned v) { return __hip_atomic_fetch_add(p, v, __ATOMIC_RELAXED, __HIP_MEMORY_SCOPE_AGENT); }
; #define XB_SPIN(cond, bar) do { unsigned _sp = 0; while (cond) { __builtin_amdgcn_s_sleep(1); \
;     if ((++_sp & 255u) == 0u) { if (xb_ld(&(bar)[XB_TMO])) break; if (_sp > XB_SPIN_CAP) { atomicAdd(&(bar)[XB_TMO], 1u); break; } } } } while (0)
; __device__ __forceinline__ void xcd_barrier(const XcdBarrier& b) {
;     ...
;         const unsigned old = xb_add(&bar[XB_XSUB(b.x)], 1u);
;         const unsigned gen = old / nloc;
;         if (old + 1u == (gen + 1u) * nloc) {
;             __builtin_amdgcn_fence(__ATOMIC_RELEASE, "agent");
;             asm volatile("s_waitcnt vmcnt(0)" ::: "memory");
;             const unsigned og = xb_add(&bar[XB_TOP], 1u);
;             const unsigned tg = og / nx;
;             if (og + 1u == (tg + 1u) * nx) xb_add(&bar[XB_TOPGEN], 1u);
;             else XB_SPIN(xb_ld(&bar[XB_TOPGEN]) == tg, bar);
;             __builtin_amdgcn_fence(__ATOMIC_ACQUIRE, "agent");
;             xb_add(&bar[XB_XGEN(b.x)], 1u);
;             asm volatile("s_waitcnt vmcnt(0)" ::: "memory");
;         } else {
;             XB_SPIN(xb_ld(&bar[XB_XGEN(b.x)]) == gen, bar);
.LBB0_77:
	v_readlane_b32 s4, v254, 3
	s_lshl_b32 s4, s4, 8
	s_add_u32 s4, s92, s4
	s_addc_u32 s5, s93, 0
	v_mov_b32_e32 v1, 0x1000
	v_mov_b32_e32 v3, 1
	global_atomic_add v3, v1, v3, s[4:5] offset:1024 sc0
	v_cvt_f32_u32_e32 v1, v2
	v_sub_u32_e32 v4, 0, v2
	v_rcp_iflag_f32_e32 v1, v1
	s_nop 0
	v_mul_f32_e32 v1, 0x4f7ffffe, v1
	v_cvt_u32_f32_e32 v1, v1
	v_mul_lo_u32 v4, v4, v1
	v_mul_hi_u32 v4, v1, v4
	v_add_u32_e32 v1, v1, v4
	s_waitcnt vmcnt(0)
	v_mul_hi_u32 v1, v3, v1
	v_mul_lo_u32 v4, v1, v2
	v_sub_u32_e32 v4, v3, v4
	v_add_u32_e32 v5, 1, v1
	v_cmp_ge_u32_e32 vcc, v4, v2
	v_add_u32_e32 v3, 1, v3
	s_nop 0
	v_cndmask_b32_e32 v1, v1, v5, vcc
	v_sub_u32_e32 v5, v4, v2
	v_cndmask_b32_e32 v4, v4, v5, vcc
	v_add_u32_e32 v5, 1, v1
	v_cmp_ge_u32_e32 vcc, v4, v2
	s_nop 1
	v_cndmask_b32_e32 v1, v1, v5, vcc
	v_mul_lo_u32 v4, v2, v1
	v_add_u32_e32 v2, v4, v2
	v_cmp_ne_u32_e32 vcc, v3, v2
	s_and_saveexec_b64 s[6:7], vcc
	s_xor_b64 s[6:7], exec, s[6:7]
	s_cbranch_execz .LBB0_91
	s_cmp_eq_u32 s101, 1
	s_cbranch_scc1 .Lsk0_nl
	s_waitcnt lgkmcnt(0)
	v_mov_b32_e32 v0, 0x2000
	global_load_dword v0, v0, s[4:5] offset:1024 sc1
	s_add_u32 s12, s4, 0x2400
	s_addc_u32 s13, s5, 0
	s_waitcnt vmcnt(0)
	v_cmp_eq_u32_e32 vcc, v0, v1
	s_and_saveexec_b64 s[8:9], vcc
	s_cbranch_execz .LBB0_90
	s_add_u32 s10, s88, 0xffc0200
	s_addc_u32 s11, s89, 0
	s_mov_b32 s24, 1
	s_mov_b64 s[14:15], 0
	v_mov_b32_e32 v0, 0
	s_branch .LBB0_81

; __device__ __forceinline__ unsigned xb_ld(unsigned* p)              { return __hip_atomic_load(p, __ATOMIC_RELAXED, __HIP_MEMORY_SCOPE_AGENT); }
; __device__ __forceinline__ unsigned xb_add(unsigned* p, unsigned v) { return __hip_atomic_fetch_add(p, v, __ATOMIC_RELAXED, __HIP_MEMORY_SCOPE_AGENT); }
; #define XB_SPIN(cond, bar) do { unsigned _sp = 0; while (cond) { __builtin_amdgcn_s_sleep(1); \
;     if ((++_sp & 255u) == 0u) { if (xb_ld(&(bar)[XB_TMO])) break; if (_sp > XB_SPIN_CAP) { atomicAdd(&(bar)[XB_TMO], 1u); break; } } } } while (0)
; __device__ __forceinline__ void xcd_barrier(const XcdBarrier& b) {
;     ...
;         const unsigned old = xb_add(&bar[XB_XSUB(b.x)], 1u);
;         const unsigned gen = old / nloc;
;         if (old + 1u == (gen + 1u) * nloc) {
;             __builtin_amdgcn_fence(__ATOMIC_RELEASE, "agent");
;             asm volatile("s_waitcnt vmcnt(0)" ::: "memory");
;             const unsigned og = xb_add(&bar[XB_TOP], 1u);
;             const unsigned tg = og / nx;
;             if (og + 1u == (tg + 1u) * nx) xb_add(&bar[XB_TOPGEN], 1u);
;             else XB_SPIN(xb_ld(&bar[XB_TOPGEN]) == tg, bar);
;             __builtin_amdgcn_fence(__ATOMIC_ACQUIRE, "agent");
;             xb_add(&bar[XB_XGEN(b.x)], 1u);
.LBB0_94:
	s_or_b64 exec, exec, s[8:9]
	v_cvt_f32_u32_e32 v3, v0
	s_waitcnt vmcnt(0)
	v_readfirstlane_b32 s6, v2
	s_add_u32 s8, s88, 0xffc3500
	s_addc_u32 s9, s89, 0
	v_rcp_iflag_f32_e32 v3, v3
	v_add_u32_e32 v1, s6, v1
	v_add_u32_e32 v4, 1, v1
	s_mov_b64 s[10:11], -1
	v_mul_f32_e32 v2, 0x4f7ffffe, v3
	v_cvt_u32_f32_e32 v2, v2
	v_sub_u32_e32 v3, 0, v0
	v_mul_lo_u32 v3, v3, v2
	v_mul_hi_u32 v3, v2, v3
	v_add_u32_e32 v2, v2, v3
	v_mul_hi_u32 v2, v1, v2
	v_mul_lo_u32 v3, v2, v0
	v_sub_u32_e32 v1, v1, v3
	v_add_u32_e32 v5, 1, v2
	v_cmp_ge_u32_e32 vcc, v1, v0
	v_sub_u32_e32 v3, v1, v0
	s_nop 0
	v_cndmask_b32_e32 v2, v2, v5, vcc
	v_cndmask_b32_e32 v1, v1, v3, vcc
	v_add_u32_e32 v3, 1, v2
	v_cmp_ge_u32_e32 vcc, v1, v0
	s_nop 1
	v_cndmask_b32_e32 v2, v2, v3, vcc
	v_mul_lo_u32 v1, v0, v2
	v_add_u32_e32 v0, v1, v0
	v_cmp_ne_u32_e32 vcc, v4, v0
	v_mov_b64_e32 v[0:1], s[8:9]
	s_and_saveexec_b64 s[6:7], vcc
	s_cbranch_execz .LBB0_106
	s_cmp_eq_u32 s101, 1
	s_cbranch_scc0 .Lsk0_ld_no
	s_mov_b64 s[14:15], 0
	s_branch .Lsk0_ld

; __device__ __forceinline__ void p0_prep(const Params& p, LAS unsigned char* lds) {
;     ...
;     for (int tI = bid; tI < 928; tI += G) {
;         const float* src; bf16_t* dst; int ldn, Kdim, ns, kt, srccol;
;         int u = tI;
;         if (u < 768) { ns = u >> 4; kt = u & 15; src = p.w_in; ldn = INW; Kdim = 1024; dst = (bf16_t*)(ws + WS_WIN); srccol = ns * 256 + (ns >= 20 ? 8 : 0); }
;         else if (u < 832) { u -= 768; ns = u >> 4; kt = u & 15; src = p.w_pm; ldn = 1024; Kdim = 1024; dst = (bf16_t*)(ws + WS_WPM); srccol = ns * 256; }
.LBB0_110:
	s_cmp_eq_u32 s101, 1
	s_cbranch_scc1 .Lp0_disp
	s_cmp_eq_u32 s101, 3
	s_cbranch_scc0 .Lp0_disp_done
.Lp0_disp:
	s_mov_b32 s99, s101
	s_mov_b32 s101, 2
	s_movk_i32 s100, 0x39f
	s_addk_i32 s84, 0x300
	v_and_b32_e32 v190, 1, v212
	s_cmpk_gt_i32 s84, 0x39f
	s_cbranch_scc0 .Lp0_reenter
.Lp0_back:
	s_addk_i32 s84, 0xfd00
	s_mov_b32 s101, 0
	s_cmp_eq_u32 s99, 1
	s_cbranch_scc0 .Lw0_done
	v_readfirstlane_b32 s96, v212
	s_nop 3
	s_cmp_lg_u32 s96, 0
	s_cbranch_scc1 .Lw0_bar
	v_readlane_b32 s96, v254, 3
	s_nop 3
	s_lshl_b32 s96, s96, 8
	v_mov_b32_e32 v250, 0xffc3500
	v_mov_b32_e32 v251, 0xffc2400
	v_add_u32_e32 v251, s96, v251
	s_mov_b32 s96, 0
.Lw0_spin:
	global_load_dword v252, v250, s[88:89] sc1
	global_load_dword v253, v251, s[88:89] sc1
	s_waitcnt vmcnt(0)
	v_min_u32_e32 v252, v252, v253
	s_nop 1
	v_readfirstlane_b32 s97, v252
	s_nop 3
	s_cmp_ge_u32 s97, 1
	s_cbranch_scc1 .Lw0_acq
	s_sleep 1
	s_add_i32 s96, s96, 1
	s_cmp_lt_u32 s96, 0x40000
	s_cbranch_scc1 .Lw0_spin

; #define PG8_STAGE(bufoff, gbase, voff) do { _Pragma("unroll") for (int _i = 0; _i < 2; ++_i) \
;         __builtin_amdgcn_global_load_lds((const unsigned*)((const char*)(gbase) + (voff)[_i]), (LAS unsigned*)(lds + (bufoff) + ldsw + _i * 8192), 16, 0, 0); } while (0)
; #define PG8_WAIT_V(n) asm volatile("s_waitcnt vmcnt(" #n ")" ::: "memory")
; template <class Epi, bool AFTER = false>
; __device__ __forceinline__ void gemm_phase(LAS unsigned char* lds, const Gemm g, const StaticOrder& S, const Epi& E) {
;     const int tid = threadIdx.x, wid = __builtin_amdgcn_readfirstlane(tid >> 6), lane = tid & 63, wr = wid >> 2, wc = wid & 3, fr = lane & 15, fq = lane >> 4;
;     const int K = g.K, nt = K / BK;
;     unsigned voffA[2], voffB[2];
; #pragma unroll
;     for (int i = 0; i < 2; ++i) { int R, C; stage_rc(tid * 16 + i * 8192, R, C); const int Rb = (R & ~31) + perm32(R & 31);
;         voffA[i] = (unsigned)(R * K + C) * 2u; voffB[i] = (unsigned)(Rb * K + C) * 2u; }
;     const size_t kstep = (size_t)(BK * 2);
;     const size_t hstep = (size_t)HALF * K * 2;
;     const size_t tstep = 2 * hstep;
;     const unsigned ldsw = (unsigned)wid * 1024u;
;     const int aoff = lds_byte(wr * 64 + fr, fq * 8), boff = lds_byte(wc * 32 + fr, fq * 8);
;     ...
;     Unit cur, nxt; int ui = 0;
;     if (!S.next(0, cur)) return;
;     f32x4 acc[2][2][4][2];
; #pragma unroll
;     for (int a = 0; a < 2; ++a)
; #pragma unroll
;         for (int b = 0; b < 2; ++b)
; #pragma unroll
;             for (int m = 0; m < 4; ++m)
; #pragma unroll
;                 for (int n = 0; n < 2; ++n) acc[a][b][m][n] = (f32x4){0.f, 0.f, 0.f, 0.f};
;     bf16x8 At[4][2], B0[2][2], B1[2][2];
;     const char* cA = (const char*)g.A + (size_t)cur.pm * tstep; const char* cB = (const char*)g.Bt + (size_t)cur.pn * tstep;
;     PG8_STAGE(PG8_SB(0, 0), cB, voffB); PG8_STAGE(PG8_SA(0, 0), cA, voffA); PG8_STAGE(PG8_SB(0, 1), cB + hstep, voffB); PG8_STAGE(PG8_SA(0, 1), cA + hstep, voffA);
;     if (wr == 1) PG8_BAR;
;     PG8_WAIT_V(4); PG8_BAR;
;     PG8_STAGE(PG8_SB(1, 0), cB + kstep, voffB); PG8_STAGE(PG8_SA(1, 0), cA + kstep, voffA); PG8_STAGE(PG8_SB(1, 1), cB + hstep + kstep, voffB);
;     PG8_WAIT_V(6); PG8_BAR;
; __global__ void __launch_bounds__(512, 2) mega_fwd(Params p) {
;     ...
;     if (IN(1)) {
;         pg8::Gemm g{H, WinT, T_TOK, 5120, 1024}; pg8::StaticOrder S; S.init(T_TOK, 5120, G, bid);
.Lw0_bar:
	s_waitcnt vmcnt(0) lgkmcnt(0)
	s_barrier
.Lw0_done:
	s_cmp_gt_i32 s91, 1
	s_cselect_b64 s[0:1], -1, 0
.Lp0_disp_done:
	s_cmp_lt_i32 s90, 2
	s_cselect_b64 s[2:3], -1, 0
	s_add_u32 s4, s88, 0x1d80000
	s_addc_u32 s5, s89, 0
	s_and_b64 s[0:1], s[2:3], s[0:1]
	v_writelane_b32 v254, s4, 20
	s_andn2_b64 vcc, exec, s[0:1]
	s_nop 0
	v_writelane_b32 v254, s5, 21
	s_cbranch_vccnz .LBB0_123
	s_cmpk_gt_i32 s84, 0x4ff
	v_readfirstlane_b32 s22, v212
	s_cbranch_scc1 .LBB0_123
	v_lshrrev_b32_e32 v2, 1, v212
	v_and_b32_e32 v11, 24, v2
	v_lshrrev_b32_e32 v2, 5, v212
	v_and_b32_e32 v2, 4, v2
	v_bfe_u32 v3, v212, 2, 2
	v_lshlrev_b32_e32 v0, 4, v212
	v_and_b32_e32 v1, 32, v212
	v_bfe_u32 v10, v212, 2, 4
	v_or3_b32 v2, v2, v3, v11
	v_lshrrev_b32_e32 v3, 3, v212
	s_movk_i32 s2, 0x70
	v_bitop3_b32 v8, v0, v1, 48 bitop3:0x6c
	v_and_b32_e32 v9, 64, v212
	v_and_or_b32 v4, v3, s2, v10
	s_movk_i32 s2, 0x60
	v_add_u32_e32 v12, 0x2000, v0
	v_or_b32_e32 v1, v8, v9
	v_and_or_b32 v3, v3, s2, v2
	v_lshrrev_b32_e32 v0, 7, v12
	s_movk_i32 s2, 0xf0
	v_lshl_or_b32 v130, v3, 11, v1
	v_and_or_b32 v3, v0, s2, v10
	s_movk_i32 s2, 0xe0
	s_ashr_i32 s24, s84, 31
	v_and_or_b32 v0, v0, s2, v2
	s_lshr_b32 s2, s24, 29
	s_add_i32 s2, s84, s2
	s_lshr_b32 s4, s22, 6
	s_ashr_i32 s5, s2, 3
	s_and_b32 s2, s2, -8
	s_lshr_b32 s3, s22, 8
	s_lshl_b32 s23, s4, 10
	s_sub_i32 s2, s84, s2
	s_cmp_lt_i32 s2, 0
	s_movk_i32 s25, 0xa1
	s_cselect_b32 s6, s25, 0xa0
	s_mul_i32 s2, s2, s6
	s_add_i32 s2, s2, s5
	s_mul_hi_i32 s5, s2, 0x66666667
	s_lshr_b32 s6, s5, 31
	s_ashr_i32 s5, s5, 5
	s_add_i32 s5, s5, s6
	s_lshl_b32 s6, s5, 2
	s_mulk_i32 s5, 0x50
	s_sub_i32 s5, s2, s5
	s_bfe_i32 s2, s5, 0x80000
	s_bfe_u32 s2, s2, 0x2000d
	s_add_i32 s7, s5, s2
	s_bfe_i32 s2, s7, 0x80000
	s_and_b32 s7, s7, 0xfc
	s_sub_i32 s5, s5, s7
	s_sext_i32_i16 s2, s2
	s_sext_i32_i8 s5, s5
	s_lshr_b32 s2, s2, 2
	s_add_i32 s6, s6, s5
	s_ashr_i32 s7, s6, 31
	s_bfe_i64 s[10:11], s[2:3], 0x100000
	s_lshl_b64 s[8:9], s[6:7], 19
	s_lshl_b64 s[10:11], s[10:11], 19
	s_add_u32 s18, s88, s10
	s_addc_u32 s19, s89, s11
	s_add_i32 s7, s23, 0
	s_add_i32 m0, s7, 0x10000
	v_lshl_or_b32 v134, v0, 11, v1
	global_load_lds_dwordx4 v130, s[18:19]
	s_add_i32 m0, s7, 0x12000
	s_add_u32 s16, s74, s8
	v_lshl_or_b32 v128, v4, 11, v1
	global_load_lds_dwordx4 v134, s[18:19]
	s_addc_u32 s17, s75, s9
	s_mov_b32 m0, s7
	s_add_i32 s26, s7, 0x2000
	v_lshl_or_b32 v132, v3, 11, v1
	global_load_lds_dwordx4 v128, s[16:17]
	s_mov_b32 m0, s26
	s_add_u32 s8, s18, 0x40000
	global_load_lds_dwordx4 v132, s[16:17]
	s_addc_u32 s9, s19, 0
	s_add_i32 m0, s7, 0x14000
	v_mov_b32_e32 v131, 0
	global_load_lds_dwordx4 v130, s[8:9]
	s_add_i32 m0, s7, 0x16000
	v_mov_b32_e32 v135, v131
	global_load_lds_dwordx4 v134, s[8:9]
	s_add_u32 s8, s16, 0x40000
	s_addc_u32 s9, s17, 0
	s_add_i32 s27, s7, 0x4000
	s_mov_b32 m0, s27
	s_add_i32 s28, s7, 0x6000
	global_load_lds_dwordx4 v128, s[8:9]
	s_mov_b32 m0, s28
	s_waitcnt lgkmcnt(0)
	v_mov_b32_e32 v129, v131
	global_load_lds_dwordx4 v132, s[8:9]
	v_mov_b32_e32 v133, v131
	s_mov_b32 s29, 0
	s_mov_b32 s100, 0
	v_lshl_add_u64 v[6:7], s[18:19], 0, v[130:131]
	v_lshl_add_u64 v[4:5], s[18:19], 0, v[134:135]
	v_lshl_add_u64 v[2:3], s[16:17], 0, v[128:129]
	s_cmp_lg_u32 s3, 1
	v_lshl_add_u64 v[0:1], s[16:17], 0, v[132:133]
	s_cbranch_scc1 .LBB0_114
	s_barrier
